# GEMM start hooks (rg_in, qkv, ffn_in): row-sum loads no longer waited at hook start; wait + conversion moved to the row-scale table write
# speedup vs baseline: 1.0130x; 1.0102x over previous
.LBB0_269:
	s_and_b64 vcc, exec, s[2:3]
	s_cbranch_vccz .LBB0_604
	v_ashrrev_i32_e32 v1, 31, v65
	v_lshrrev_b32_e32 v1, 26, v1
	v_add_u32_e32 v1, v65, v1
	v_ashrrev_i32_e32 v56, 6, v1
	v_bfe_i32 v1, v65, 27, 1
	v_lshlrev_b32_e32 v0, 4, v65
	v_lshrrev_b32_e32 v1, 22, v1
	v_add_u32_e32 v1, v0, v1
	v_and_b32_e32 v1, 0xfffffc00, v1
	v_sub_u32_e32 v1, v0, v1
	v_lshrrev_b32_e32 v2, 4, v1
	v_bitop3_b32 v1, v2, v1, 32 bitop3:0x6c
	v_ashrrev_i32_e32 v3, 31, v1
	v_lshrrev_b32_e32 v3, 26, v3
	v_add_u32_e32 v3, v1, v3
	v_ashrrev_i32_e32 v57, 6, v3
	v_and_b32_e32 v3, 0xc0, v3
	v_sub_u32_e32 v1, v1, v3
	v_lshlrev_b32_e32 v2, 3, v56
	v_lshlrev_b32_e32 v4, 5, v56
	v_ashrrev_i16_sdwa v1, v215, sext(v1) dst_sel:DWORD dst_unused:UNUSED_PAD src0_sel:DWORD src1_sel:BYTE_0
	v_and_b32_e32 v2, 0x1ffff0, v2
	v_and_b32_e32 v4, 32, v4
	v_bfe_i32 v58, v1, 0, 16
	v_add_u32_e32 v1, v4, v58
	v_add_lshl_u32 v2, v57, v2, 11
	v_add_u32_e32 v0, 0x2000, v0
	v_lshl_add_u32 v140, v1, 1, v2
	v_ashrrev_i32_e32 v1, 31, v0
	v_lshrrev_b32_e32 v1, 22, v1
	v_add_u32_e32 v1, v0, v1
	s_ashr_i32 s74, s17, 6
	v_ashrrev_i32_e32 v59, 10, v1
	v_mul_i32_i24_e32 v1, 0x400, v59
	s_lshl_b32 s13, s74, 10
	v_sub_u32_e32 v0, v0, v1
	s_add_u32 s14, s56, 0x9d00000
	v_readlane_b32 s2, v254, 49
	v_lshrrev_b32_e32 v1, 4, v0
	s_addc_u32 s15, s57, 0
	s_lshl_b32 s2, s2, 18
	v_bitop3_b32 v0, v1, v0, 32 bitop3:0x6c
	v_readlane_b32 s3, v254, 50
	s_add_u32 s2, s56, s2
	v_writelane_b32 v255, s42, 16
	v_ashrrev_i32_e32 v2, 31, v0
	s_addc_u32 s3, s57, 0
	v_writelane_b32 v255, s43, 17
	v_lshrrev_b32_e32 v2, 26, v2
	s_add_u32 s42, s2, 0x100000
	v_add_u32_e32 v2, v0, v2
	s_addc_u32 s43, s3, 0
	s_ashr_i32 s5, s4, 31
	s_ashr_i32 s7, s6, 31
	v_ashrrev_i32_e32 v60, 6, v2
	v_and_b32_e32 v2, 0xc0, v2
	s_lshl_b64 s[2:3], s[4:5], 19
	s_lshl_b64 s[28:29], s[6:7], 19
	v_readlane_b32 s5, v254, 53
	v_sub_u32_e32 v0, v0, v2
	s_add_u32 s64, s5, s28
	v_lshlrev_b32_e32 v1, 3, v59
	v_lshlrev_b32_e32 v3, 5, v59
	v_ashrrev_i16_sdwa v0, v215, sext(v0) dst_sel:DWORD dst_unused:UNUSED_PAD src0_sel:DWORD src1_sel:BYTE_0
	s_addc_u32 s65, s18, s29
	s_add_i32 s7, s13, 0
	v_and_b32_e32 v1, 0x1ffff0, v1
	v_and_b32_e32 v3, 32, v3
	v_bfe_i32 v61, v0, 0, 16
	s_add_i32 m0, s7, 0x10000
	v_add_u32_e32 v0, v3, v61
	v_add_lshl_u32 v1, v60, v1, 11
	global_load_lds_dwordx4 v140, s[64:65]
	s_add_i32 m0, s7, 0x12000
	v_lshl_add_u32 v142, v0, 1, v1
	s_add_u32 s28, s64, 0x40000
	global_load_lds_dwordx4 v142, s[64:65]
	s_addc_u32 s29, s65, 0
	s_add_i32 m0, s7, 0x14000
	s_mov_b32 s23, s17
	global_load_lds_dwordx4 v140, s[28:29]
	s_add_i32 m0, s7, 0x16000
	s_add_u32 s66, s14, s2
	s_addc_u32 s67, s15, s3
	s_add_i32 s17, s7, 0x2000
	global_load_lds_dwordx4 v142, s[28:29]
	s_mov_b32 m0, s7
	s_add_u32 s2, s66, 0x40000
	global_load_lds_dwordx4 v140, s[66:67]
	s_mov_b32 m0, s17
	s_addc_u32 s3, s67, 0
	s_add_i32 s72, s7, 0x4000
	global_load_lds_dwordx4 v142, s[66:67]
	s_mov_b32 m0, s72
	s_add_i32 s73, s7, 0x6000
	global_load_lds_dwordx4 v140, s[2:3]
	s_mov_b32 m0, s73
	v_mov_b32_e32 v62, 0x358637bd
	global_load_lds_dwordx4 v142, s[2:3]
	s_movk_i32 s2, 0x100
	v_cmp_gt_i32_e64 s[38:39], s2, v64
	s_and_saveexec_b64 s[2:3], s[38:39]
	s_cbranch_execz .LBB0_272
	v_add_u32_e32 v0, s77, v64
	v_ashrrev_i32_e32 v1, 31, v0
	v_lshl_add_u64 v[0:1], v[0:1], 3, s[42:43]
	global_load_dwordx2 v[152:153], v[0:1], off

.LBB0_368:
	s_waitcnt vmcnt(0)
	v_ffbh_u32_e32 v166, v153
	v_min_u32_e32 v166, 32, v166
	v_lshlrev_b64 v[164:165], v166, v[152:153]
	v_min_u32_e32 v164, 1, v164
	v_or_b32_e32 v164, v165, v164
	v_cvt_f32_u32_e32 v164, v164
	v_sub_u32_e32 v165, 32, v166
	v_ldexp_f32 v164, v164, v165
	v_fmamk_f32 v62, v164, 0x2e800000, v214
	s_and_saveexec_b64 s[2:3], s[38:39]
	s_cbranch_execz .LBB0_370
	v_rsq_f32_e32 v0, v62
	v_lshl_add_u32 v1, v64, 2, 0
	v_add_u32_e32 v1, 0x22500, v1
	ds_write_b32 v1, v0

.LBB0_1596:
	s_and_b64 vcc, exec, s[0:1]
	s_cbranch_vccz .LBB0_1772
	v_lshlrev_b32_e32 v0, 4, v65
	v_add_u32_e32 v1, 0x2000, v0
	v_ashrrev_i32_e32 v2, 31, v1
	v_lshrrev_b32_e32 v2, 22, v2
	v_add_u32_e32 v2, v1, v2
	v_ashrrev_i32_e32 v56, 10, v2
	v_mul_i32_i24_e32 v2, 0x400, v56
	v_sub_u32_e32 v1, v1, v2
	v_lshrrev_b32_e32 v2, 4, v1
	v_writelane_b32 v254, s30, 59
	s_ashr_i32 s90, s16, 6
	v_bitop3_b32 v1, v2, v1, 32 bitop3:0x6c
	v_writelane_b32 v254, s31, 60
	s_lshl_b32 s18, s90, 10
	v_ashrrev_i32_e32 v2, 31, v1
	s_add_u32 s28, s4, 0x9d00000
	v_readlane_b32 s0, v254, 49
	v_lshrrev_b32_e32 v2, 26, v2
	s_addc_u32 s29, s5, 0
	s_lshl_b32 s0, s0, 18
	v_add_u32_e32 v2, v1, v2
	v_lshlrev_b32_e32 v3, 3, v56
	v_readlane_b32 s1, v254, 50
	s_add_u32 s0, s4, s0
	v_ashrrev_i32_e32 v57, 6, v2
	v_and_b32_e32 v3, -16, v3
	s_addc_u32 s1, s5, 0
	v_add_u32_e32 v3, v57, v3
	s_add_u32 s44, s0, 0x100000
	v_and_b32_e32 v4, 3, v57
	s_mov_b32 s0, 0x1fffe0
	v_lshrrev_b32_e32 v5, 2, v3
	v_lshlrev_b32_e32 v6, 1, v3
	v_and_b32_e32 v2, 0xc0, v2
	v_and_or_b32 v4, v3, s0, v4
	v_and_b32_e32 v5, 4, v5
	v_and_b32_e32 v6, 24, v6
	v_sub_u32_e32 v1, v1, v2
	v_or3_b32 v4, v4, v5, v6
	v_lshlrev_b32_e32 v5, 5, v56
	v_ashrrev_i16_sdwa v1, v215, sext(v1) dst_sel:DWORD dst_unused:UNUSED_PAD src0_sel:DWORD src1_sel:BYTE_0
	v_and_b32_e32 v5, 32, v5
	v_bfe_i32 v58, v1, 0, 16
	v_add_lshl_u32 v1, v5, v58, 1
	v_lshl_add_u32 v138, v4, 11, v1
	v_lshl_add_u32 v140, v3, 11, v1
	v_bfe_i32 v1, v65, 27, 1
	v_lshrrev_b32_e32 v1, 22, v1
	v_add_u32_e32 v1, v0, v1
	v_and_b32_e32 v1, 0xfffffc00, v1
	v_sub_u32_e32 v0, v0, v1
	v_lshrrev_b32_e32 v1, 4, v0
	v_ashrrev_i32_e32 v2, 31, v65
	v_bitop3_b32 v0, v1, v0, 32 bitop3:0x6c
	v_lshrrev_b32_e32 v2, 26, v2
	v_ashrrev_i32_e32 v1, 31, v0
	v_add_u32_e32 v2, v65, v2
	v_lshrrev_b32_e32 v1, 26, v1
	v_ashrrev_i32_e32 v60, 6, v2
	v_add_u32_e32 v1, v0, v1
	v_lshlrev_b32_e32 v2, 3, v60
	v_ashrrev_i32_e32 v59, 6, v1
	v_and_b32_e32 v2, -16, v2
	v_add_u32_e32 v2, v59, v2
	v_and_b32_e32 v3, 3, v59
	v_lshrrev_b32_e32 v4, 2, v2
	v_lshlrev_b32_e32 v5, 1, v2
	v_and_b32_e32 v1, 0xc0, v1
	s_addc_u32 s45, s1, 0
	v_and_or_b32 v3, v2, s0, v3
	v_and_b32_e32 v4, 4, v4
	v_and_b32_e32 v5, 24, v5
	v_sub_u32_e32 v0, v0, v1
	s_ashr_i32 s7, s6, 31
	s_ashr_i32 s43, s42, 31
	v_or3_b32 v3, v3, v4, v5
	v_lshlrev_b32_e32 v4, 5, v60
	v_ashrrev_i16_sdwa v0, v215, sext(v0) dst_sel:DWORD dst_unused:UNUSED_PAD src0_sel:DWORD src1_sel:BYTE_0
	s_lshl_b64 s[0:1], s[6:7], 19
	s_lshl_b64 s[2:3], s[42:43], 19
	v_and_b32_e32 v4, 32, v4
	v_bfe_i32 v61, v0, 0, 16
	s_add_u32 s66, s15, s2
	v_add_lshl_u32 v0, v4, v61, 1
	s_addc_u32 s67, s17, s3
	s_add_i32 s7, s18, 0
	v_lshl_add_u32 v142, v3, 11, v0
	s_add_i32 m0, s7, 0x10000
	v_lshl_add_u32 v144, v2, 11, v0
	global_load_lds_dwordx4 v142, s[66:67]
	s_add_i32 m0, s7, 0x12000
	s_add_u32 s2, s66, 0x40000
	global_load_lds_dwordx4 v138, s[66:67]
	s_addc_u32 s3, s67, 0
	s_add_i32 m0, s7, 0x14000
	v_mov_b32_e32 v62, 0x358637bd
	global_load_lds_dwordx4 v142, s[2:3]
	s_add_i32 m0, s7, 0x16000
	s_add_u32 s46, s28, s0
	s_addc_u32 s47, s29, s1
	s_add_i32 s30, s7, 0x2000
	global_load_lds_dwordx4 v138, s[2:3]
	s_mov_b32 m0, s7
	s_add_u32 s0, s46, 0x40000
	global_load_lds_dwordx4 v144, s[46:47]
	s_mov_b32 m0, s30
	s_addc_u32 s1, s47, 0
	s_add_i32 s31, s7, 0x4000
	global_load_lds_dwordx4 v140, s[46:47]
	s_mov_b32 m0, s31
	s_add_i32 s43, s7, 0x6000
	global_load_lds_dwordx4 v144, s[0:1]
	s_mov_b32 m0, s43
	s_nop 0
	global_load_lds_dwordx4 v140, s[0:1]
	s_movk_i32 s0, 0x100
	v_cmp_gt_i32_e64 s[36:37], s0, v64
	s_and_saveexec_b64 s[0:1], s[36:37]
	s_cbranch_execz .LBB0_1599
	v_add_u32_e32 v0, s71, v64
	v_ashrrev_i32_e32 v1, 31, v0
	v_lshl_add_u64 v[0:1], v[0:1], 3, s[44:45]
	global_load_dwordx2 v[136:137], v[0:1], off

.LBB0_1675:
	s_waitcnt vmcnt(0)
	v_ffbh_u32_e32 v152, v137
	v_min_u32_e32 v152, 32, v152
	v_lshlrev_b64 v[146:147], v152, v[136:137]
	v_min_u32_e32 v146, 1, v146
	v_or_b32_e32 v146, v147, v146
	v_cvt_f32_u32_e32 v146, v146
	v_sub_u32_e32 v147, 32, v152
	v_ldexp_f32 v146, v146, v147
	v_fmamk_f32 v62, v146, 0x2e800000, v214
	s_and_saveexec_b64 s[0:1], s[36:37]
	s_cbranch_execz .LBB0_1677
	v_rsq_f32_e32 v0, v62
	v_lshl_add_u32 v1, v64, 2, 0
	v_add_u32_e32 v1, 0x22500, v1
	ds_write_b32 v1, v0

.LBB0_2320:
	s_ashr_i32 s21, s2, 6
	s_add_u32 s44, s6, 0x9d00000
	v_readlane_b32 s40, v254, 49
	s_addc_u32 s79, s7, 0
	s_lshl_b32 s0, s40, 18
	s_add_u32 s0, s6, s0
	s_addc_u32 s1, s7, 0
	s_add_u32 s4, s0, 0x120000
	v_writelane_b32 v255, s8, 20
	s_addc_u32 s5, s1, 0
	s_lshl_b32 s8, s40, 6
	s_lshl_b64 s[0:1], s[8:9], 3
	s_add_u32 s0, s6, s0
	s_addc_u32 s1, s7, s1
	s_add_u32 s28, s0, 0x240100
	s_addc_u32 s29, s1, 0
	s_add_u32 s1, s6, 0x1100000
	s_addc_u32 s3, s7, 0
	s_mul_i32 s0, s40, 0xb00000
	s_add_u32 s0, s1, s0
	v_writelane_b32 v255, s1, 7
	s_addc_u32 s1, s3, 0
	v_readlane_b32 s41, v254, 50
	s_add_u32 s66, s6, 0x11d00000
	s_addc_u32 s67, s7, 0
	s_and_b32 s41, s2, 0xffffffc0
	v_readlane_b32 s36, v253, 35
	v_ashrrev_i32_e32 v0, 5, v79
	s_cmp_lt_i32 s18, 1
	v_readlane_b32 s37, v253, 36
	v_ashrrev_i32_e32 v1, 31, v0
	s_cselect_b64 s[30:31], -1, 0
	s_xor_b64 s[36:37], s[36:37], -1
	v_lshl_add_u64 v[38:39], v[0:1], 3, s[28:29]
	v_add_u32_e32 v1, 0x200, v79
	s_or_b64 s[42:43], s[36:37], s[30:31]
	v_ashrrev_i32_e32 v2, 5, v1
	s_movk_i32 s8, 0x100
	s_add_u32 s86, s6, 0x24b80000
	v_ashrrev_i32_e32 v3, 31, v2
	v_cmp_gt_i32_e64 s[30:31], s8, v79
	s_movk_i32 s8, 0x80
	s_addc_u32 s87, s7, 0
	v_lshl_add_u64 v[40:41], v[2:3], 3, s[28:29]
	v_and_b32_e32 v80, 31, v79
	s_lshl_b32 s28, s21, 7
	v_cmp_gt_i32_e64 s[84:85], s8, v79
	v_readlane_b32 s8, v251, 0
	v_lshlrev_b32_e32 v32, 11, v80
	s_ashr_i32 s29, s28, 31
	s_add_i32 s46, s45, s8
	v_lshl_add_u64 v[4:5], s[6:7], 0, v[32:33]
	s_lshl_b64 s[28:29], s[28:29], 1
	v_lshl_add_u64 v[4:5], v[4:5], 0, s[28:29]
	s_add_u32 s28, s0, s28
	v_bfe_u32 v1, v79, 5, 1
	s_addc_u32 s29, s1, s29
	s_lshl_b32 s8, s21, 12
	v_lshlrev_b32_e32 v32, 4, v1
	s_add_i32 s8, s8, 0
	v_lshlrev_b32_e32 v1, 9, v1
	v_lshlrev_b32_e32 v81, 2, v80
	v_add3_u32 v82, s8, v1, v81
	s_movk_i32 s8, 0x800
	v_cmp_gt_i32_e64 s[38:39], s8, v79
	s_movk_i32 s8, 0x84
	s_movk_i32 s12, 0xb00
	v_mul_lo_u32 v1, v0, s8
	v_mul_lo_u32 v0, v0, s12
	v_or_b32_e32 v101, v0, v80
	v_mul_lo_u32 v0, v2, s8
	s_cmp_lg_u32 s40, 3
	v_readlane_b32 s8, v253, 41
	v_writelane_b32 v254, s30, 59
	s_cselect_b64 s[90:91], -1, 0
	s_add_i32 s34, s8, s11
	s_lshl_b32 s11, s45, 4
	v_writelane_b32 v254, s31, 60
	v_lshl_add_u64 v[4:5], v[4:5], 0, v[32:33]
	s_mov_b64 s[30:31], 0x24b20000
	s_lshl_b32 s8, s45, 3
	s_addk_i32 s11, 0xfd00
	v_lshl_add_u64 v[42:43], v[4:5], 0, s[30:31]
	s_add_i32 s30, s45, 0xffffffa8
	s_add_i32 s8, s8, s11
	s_cmp_eq_u32 s40, 1
	s_movk_i32 s15, 0x5900
	v_add3_u32 v102, s27, v0, v81
	v_mul_lo_u32 v0, v2, s12
	s_cselect_b32 s12, 0x4480, s15
	s_cmp_lg_u32 s40, 0
	s_cselect_b32 s16, s12, 0x2e00
	s_add_i32 s51, s8, 0xfffffd40
	s_cmp_lt_i32 s21, 3
	s_mul_i32 s8, s21, 0x2100
	s_mov_b32 s12, 0x8000
	s_cselect_b32 s12, s12, 0x11d00
	s_add_i32 s8, s8, 0
	v_writelane_b32 v255, s3, 8
	s_add_i32 s8, s8, s12
	s_add_i32 s11, s11, s21
	v_writelane_b32 v255, s11, 21
	s_cmp_eq_u32 s40, 2
	s_movk_i32 s11, 0xa700
	s_cselect_b32 s11, 0xffffbb80, s11
	s_cselect_b32 s36, 0x4480, s15
	s_add_u32 s96, s6, 0x5b00000
	s_addc_u32 s97, s7, 0
	v_lshl_add_u64 v[44:45], s[28:29], 0, v[32:33]
	s_add_u32 s28, s6, 0x5700000
	v_writelane_b32 v255, s11, 22
	s_addc_u32 s29, s7, 0
	v_writelane_b32 v255, s28, 23
	v_add3_u32 v100, s27, v1, v81
	v_lshlrev_b32_e32 v1, 3, v79
	v_writelane_b32 v255, s29, 24
	s_add_u32 s28, s6, 0x5900000
	s_addc_u32 s29, s7, 0
	v_writelane_b32 v255, s28, 25
	v_or_b32_e32 v103, v0, v80
	v_bfe_u32 v66, v79, 3, 3
	v_writelane_b32 v255, s29, 26
	s_add_u32 s28, s6, 0x5300000
	s_addc_u32 s29, s7, 0
	v_writelane_b32 v255, s28, 14
	s_add_u32 s11, s6, 0x3d00000
	v_lshlrev_b32_e32 v0, 2, v79
	v_writelane_b32 v255, s29, 15
	v_writelane_b32 v255, s11, 5
	s_addc_u32 s11, s7, 0
	v_writelane_b32 v255, s11, 3
	s_add_u32 s11, s6, 0xd00000
	v_writelane_b32 v254, s11, 53
	s_addc_u32 s11, s7, 0
	s_add_u32 s12, s6, 0xc00000
	v_writelane_b32 v254, s11, 55
	s_addc_u32 s11, s7, 0
	s_add_u32 s23, s6, 0x400000
	s_addc_u32 s15, s7, 0
	s_and_b32 s21, s21, 7
	s_lshl_b32 s28, s21, 5
	s_lshl_b32 s17, s30, 3
	s_add_i32 s29, s28, 0xffffff80
	v_and_b32_e32 v94, 56, v1
	s_cmp_lt_u32 s21, 4
	v_and_b32_e32 v67, 28, v0
	v_mul_u32_u24_e32 v1, 0x84, v94
	v_lshlrev_b32_e32 v2, 2, v66
	s_cselect_b32 s21, s28, s29
	v_lshl_add_u32 v76, v67, 2, s8
	v_add3_u32 v78, s8, v1, v2
	s_add_i32 s8, 0, 0x22500
	v_add_u32_e32 v71, s8, v0
	s_add_i32 s8, 0, 0x22900
	v_add_u32_e32 v65, s8, v0
	v_mbcnt_lo_u32_b32 v0, -1, 0
	v_mbcnt_hi_u32_b32 v0, -1, v0
	v_writelane_b32 v254, s41, 61
	v_add_u32_e32 v64, s41, v0
	s_mov_b64 s[2:3], -1
	v_add_u32_e32 v83, 0x18000, v82
	v_add_u32_e32 v84, 0x18080, v82
	v_add_u32_e32 v85, 0x18100, v82
	v_add_u32_e32 v86, 0x18180, v82
	v_add_u32_e32 v87, 0x18400, v82
	v_add_u32_e32 v88, 0x18480, v82
	v_add_u32_e32 v89, 0x18500, v82
	v_add_u32_e32 v90, 0x18580, v82
	v_add_u32_e32 v91, 0x18800, v82
	v_add_u32_e32 v92, 0x18880, v82
	v_add_u32_e32 v93, 0x18900, v82
	v_add_u32_e32 v95, 0x18980, v82
	v_add_u32_e32 v96, 0x18c00, v82
	v_add_u32_e32 v97, 0x18c80, v82
	v_add_u32_e32 v98, 0x18d00, v82
	v_add_u32_e32 v99, 0x18d80, v82
	v_or_b32_e32 v68, 8, v66
	v_or_b32_e32 v69, 16, v66
	v_or_b32_e32 v70, 24, v66
	v_or_b32_e32 v72, 32, v66
	v_or_b32_e32 v73, 40, v66
	v_or_b32_e32 v74, 48, v66
	v_or_b32_e32 v75, 56, v66
	v_mul_u32_u24_e32 v77, 0x84, v66
	s_and_b64 vcc, exec, s[42:43]
	v_readfirstlane_b32 s50, v64
	v_writelane_b32 v254, s45, 57
	s_mov_b64 s[40:41], s[66:67]
	s_mov_b32 s37, s44
	s_cbranch_vccz .LBB0_2424
	v_readlane_b32 s2, v253, 35
	v_readlane_b32 s28, v254, 59
	v_readlane_b32 s3, v253, 36
	v_readlane_b32 s29, v254, 60
	v_mov_b32_e32 v104, 0x358637bd
	v_mov_b32_e32 v105, 0x358637bd
	s_and_b64 s[28:29], s[2:3], s[28:29]
	s_mov_b64 s[2:3], exec
	v_writelane_b32 v255, s28, 27
	s_nop 1
	v_writelane_b32 v255, s29, 28
	s_and_b64 s[28:29], s[2:3], s[28:29]
	s_mov_b64 exec, s[28:29]
	s_cbranch_execz .LBB0_2323
	v_add_u32_e32 v0, s35, v79
	v_ashrrev_i32_e32 v1, 31, v0
	v_lshl_add_u64 v[0:1], v[0:1], 3, s[4:5]
	global_load_dwordx2 v[106:107], v[0:1], off
.LBB0_2323:
	v_writelane_b32 v255, s50, 29
	s_or_b64 exec, exec, s[2:3]
	s_and_b64 s[64:65], s[92:93], s[84:85]
	s_and_saveexec_b64 s[2:3], s[64:65]
	s_cbranch_execz .LBB0_2325
	v_readlane_b32 s8, v254, 51
	s_add_i32 s8, s83, s8
	s_nop 0
	v_add_u32_e32 v0, s8, v79
	v_ashrrev_i32_e32 v1, 31, v0
	v_lshl_add_u64 v[0:1], v[0:1], 3, s[4:5]
	global_load_dwordx2 v[108:109], v[0:1], off

.LBB0_2419:
	s_waitcnt vmcnt(0)
	v_ffbh_u32_e32 v112, v107
	v_min_u32_e32 v112, 32, v112
	v_lshlrev_b64 v[110:111], v112, v[106:107]
	v_min_u32_e32 v110, 1, v110
	v_or_b32_e32 v110, v111, v110
	v_cvt_f32_u32_e32 v110, v110
	v_sub_u32_e32 v111, 32, v112
	v_ldexp_f32 v110, v110, v111
	v_fmamk_f32 v105, v110, 0x2e800000, v214
	v_ffbh_u32_e32 v112, v109
	v_min_u32_e32 v112, 32, v112
	v_lshlrev_b64 v[110:111], v112, v[108:109]
	v_min_u32_e32 v110, 1, v110
	v_or_b32_e32 v110, v111, v110
	v_cvt_f32_u32_e32 v110, v110
	v_sub_u32_e32 v111, 32, v112
	v_ldexp_f32 v110, v110, v111
	v_fmamk_f32 v104, v110, 0x2e800000, v214
	s_mov_b64 s[2:3], exec
	v_readlane_b32 s28, v255, 27
	v_readlane_b32 s29, v255, 28
	s_and_b64 s[28:29], s[2:3], s[28:29]
	s_mov_b64 exec, s[28:29]
	v_rsq_f32_e32 v0, v105
	ds_write_b32 v71, v0
	s_or_b64 exec, exec, s[2:3]
	s_and_saveexec_b64 s[2:3], s[64:65]
	v_readlane_b32 s50, v255, 29
	v_rsq_f32_e32 v0, v104
	ds_write_b32 v65, v0
	s_or_b64 exec, exec, s[2:3]
	s_mov_b64 s[2:3], 0
	s_waitcnt lgkmcnt(0)
	s_barrier
.LBB0_2424:
	s_and_b64 vcc, exec, s[2:3]
	s_cbranch_vccz .LBB0_2547
	v_lshlrev_b32_e32 v0, 4, v64
	v_add_u32_e32 v1, 0x2000, v0
	v_ashrrev_i32_e32 v2, 31, v1
	v_lshrrev_b32_e32 v2, 22, v2
	v_add_u32_e32 v2, v1, v2
	v_ashrrev_i32_e32 v56, 10, v2
	v_mul_i32_i24_e32 v2, 0x400, v56
	v_sub_u32_e32 v1, v1, v2
	v_lshrrev_b32_e32 v2, 4, v1
	v_bitop3_b32 v1, v2, v1, 32 bitop3:0x6c
	v_ashrrev_i32_e32 v2, 31, v1
	v_lshrrev_b32_e32 v2, 26, v2
	v_add_u32_e32 v2, v1, v2
	v_lshlrev_b32_e32 v3, 3, v56
	v_ashrrev_i32_e32 v57, 6, v2
	v_and_b32_e32 v3, -16, v3
	v_add_u32_e32 v3, v57, v3
	v_and_b32_e32 v4, 3, v57
	s_mov_b32 s2, 0x1fffe0
	v_lshrrev_b32_e32 v5, 2, v3
	v_lshlrev_b32_e32 v6, 1, v3
	v_and_b32_e32 v2, 0xc0, v2
	v_and_or_b32 v4, v3, s2, v4
	v_and_b32_e32 v5, 4, v5
	v_and_b32_e32 v6, 24, v6
	v_sub_u32_e32 v1, v1, v2
	v_or3_b32 v4, v4, v5, v6
	v_lshlrev_b32_e32 v5, 5, v56
	v_ashrrev_i16_sdwa v1, v215, sext(v1) dst_sel:DWORD dst_unused:UNUSED_PAD src0_sel:DWORD src1_sel:BYTE_0
	v_and_b32_e32 v5, 32, v5
	v_bfe_i32 v58, v1, 0, 16
	v_add_lshl_u32 v1, v5, v58, 1
	v_lshl_add_u32 v130, v4, 11, v1
	v_lshl_add_u32 v132, v3, 11, v1
	v_bfe_i32 v1, v64, 27, 1
	v_lshrrev_b32_e32 v1, 22, v1
	v_add_u32_e32 v1, v0, v1
	v_and_b32_e32 v1, 0xfffffc00, v1
	v_sub_u32_e32 v0, v0, v1
	v_lshrrev_b32_e32 v1, 4, v0
	v_ashrrev_i32_e32 v2, 31, v64
	v_bitop3_b32 v0, v1, v0, 32 bitop3:0x6c
	v_lshrrev_b32_e32 v2, 26, v2
	v_ashrrev_i32_e32 v1, 31, v0
	v_add_u32_e32 v2, v64, v2
	v_lshrrev_b32_e32 v1, 26, v1
	v_ashrrev_i32_e32 v60, 6, v2
	v_add_u32_e32 v1, v0, v1
	v_lshlrev_b32_e32 v2, 3, v60
	v_ashrrev_i32_e32 v59, 6, v1
	v_and_b32_e32 v2, -16, v2
	v_add_u32_e32 v2, v59, v2
	v_and_b32_e32 v3, 3, v59
	v_lshrrev_b32_e32 v4, 2, v2
	v_lshlrev_b32_e32 v5, 1, v2
	v_and_b32_e32 v1, 0xc0, v1
	s_ashr_i32 s47, s50, 6
	v_and_or_b32 v3, v2, s2, v3
	v_and_b32_e32 v4, 4, v4
	v_and_b32_e32 v5, 24, v5
	v_sub_u32_e32 v0, v0, v1
	s_lshl_b32 s74, s47, 10
	v_or3_b32 v3, v3, v4, v5
	v_lshlrev_b32_e32 v4, 5, v60
	v_ashrrev_i16_sdwa v0, v215, sext(v0) dst_sel:DWORD dst_unused:UNUSED_PAD src0_sel:DWORD src1_sel:BYTE_0
	v_readlane_b32 s2, v253, 55
	v_and_b32_e32 v4, 32, v4
	v_bfe_i32 v61, v0, 0, 16
	v_readlane_b32 s3, v253, 56
	s_add_u32 s42, s0, s2
	v_add_lshl_u32 v0, v4, v61, 1
	s_addc_u32 s43, s1, s3
	s_add_i32 s75, s74, 0
	v_lshl_add_u32 v134, v3, 11, v0
	s_add_i32 m0, s75, 0x10000
	v_lshl_add_u32 v136, v2, 11, v0
	global_load_lds_dwordx4 v134, s[42:43]
	s_add_i32 m0, s75, 0x12000
	s_add_u32 s2, s42, 0x40000
	global_load_lds_dwordx4 v130, s[42:43]
	s_addc_u32 s3, s43, 0
	s_add_i32 m0, s75, 0x14000
	v_mov_b32_e32 v62, 0x358637bd
	global_load_lds_dwordx4 v134, s[2:3]
	s_add_i32 m0, s75, 0x16000
	v_mov_b32_e32 v63, 0x358637bd
	global_load_lds_dwordx4 v130, s[2:3]
	v_readlane_b32 s2, v253, 59
	v_readlane_b32 s3, v253, 60
	s_add_u32 s62, s44, s2
	s_addc_u32 s63, s79, s3
	s_add_i32 s76, s75, 0x2000
	s_mov_b32 m0, s75
	s_add_u32 s2, s62, 0x40000
	global_load_lds_dwordx4 v136, s[62:63]
	s_mov_b32 m0, s76
	s_addc_u32 s3, s63, 0
	s_add_i32 s77, s75, 0x4000
	global_load_lds_dwordx4 v132, s[62:63]
	s_mov_b32 m0, s77
	s_add_i32 s78, s75, 0x6000
	global_load_lds_dwordx4 v136, s[2:3]
	s_mov_b32 m0, s78
	s_nop 0
	global_load_lds_dwordx4 v132, s[2:3]
	s_mov_b64 s[2:3], exec
	v_readlane_b32 s28, v254, 59
	v_readlane_b32 s29, v254, 60
	s_and_b64 s[28:29], s[2:3], s[28:29]
	s_mov_b64 exec, s[28:29]
	s_cbranch_execz .LBB0_2427
	v_add_u32_e32 v0, s35, v79
	v_ashrrev_i32_e32 v1, 31, v0
	v_lshl_add_u64 v[0:1], v[0:1], 3, s[4:5]
	global_load_dwordx2 v[104:105], v[0:1], off
.LBB0_2427:
	s_or_b64 exec, exec, s[2:3]
	s_and_b64 s[48:49], s[92:93], s[84:85]
	s_and_saveexec_b64 s[2:3], s[48:49]
	s_movk_i32 s35, 0x5ff
	s_cbranch_execz .LBB0_2429
	v_readlane_b32 s8, v254, 51
	s_add_i32 s8, s83, s8
	s_nop 0
	v_add_u32_e32 v0, s8, v79
	v_ashrrev_i32_e32 v1, 31, v0
	v_lshl_add_u64 v[0:1], v[0:1], 3, s[4:5]
	global_load_dwordx2 v[106:107], v[0:1], off

.LBB0_2523:
	s_waitcnt vmcnt(0)
	v_ffbh_u32_e32 v128, v105
	v_min_u32_e32 v128, 32, v128
	v_lshlrev_b64 v[110:111], v128, v[104:105]
	v_min_u32_e32 v110, 1, v110
	v_or_b32_e32 v110, v111, v110
	v_cvt_f32_u32_e32 v110, v110
	v_sub_u32_e32 v111, 32, v128
	v_ldexp_f32 v110, v110, v111
	v_fmamk_f32 v63, v110, 0x2e800000, v214
	v_ffbh_u32_e32 v128, v107
	v_min_u32_e32 v128, 32, v128
	v_lshlrev_b64 v[110:111], v128, v[106:107]
	v_min_u32_e32 v110, 1, v110
	v_or_b32_e32 v110, v111, v110
	v_cvt_f32_u32_e32 v110, v110
	v_sub_u32_e32 v111, 32, v128
	v_ldexp_f32 v110, v110, v111
	v_fmamk_f32 v62, v110, 0x2e800000, v214
	s_mov_b64 s[2:3], exec
	v_readlane_b32 s20, v254, 59
	v_readlane_b32 s21, v254, 60
	s_and_b64 s[20:21], s[2:3], s[20:21]
	s_mov_b64 exec, s[20:21]
	v_rsq_f32_e32 v0, v63
	ds_write_b32 v71, v0
	s_or_b64 exec, exec, s[2:3]
	s_and_saveexec_b64 s[2:3], s[48:49]
	v_rsq_f32_e32 v0, v62
	ds_write_b32 v65, v0
	s_or_b64 exec, exec, s[2:3]
	s_ashr_i32 s2, s31, 8
	s_cmp_eq_u32 s2, 1
	v_mov_b32_e32 v135, v33
	v_mov_b32_e32 v131, v33
	v_mov_b32_e32 v137, v33
	v_mov_b32_e32 v133, v33
	s_cselect_b64 s[36:37], -1, 0
	v_lshl_add_u64 v[4:5], s[42:43], 0, v[134:135]
	v_lshl_add_u64 v[6:7], s[42:43], 0, v[130:131]
	v_lshl_add_u64 v[2:3], s[62:63], 0, v[136:137]
	v_lshl_add_u64 v[0:1], s[62:63], 0, v[132:133]
	s_and_b64 vcc, exec, s[36:37]
	s_waitcnt vmcnt(0) lgkmcnt(0)
	s_barrier
	s_cbranch_vccz .LBB0_2529
	s_barrier
